# m3: cross-chunk software prefetch (all loads of chunk i+1 issued before chunk i's barrier 1; tail moved to low registers; counted waits)
# speedup vs baseline: 1.0000x; 1.0000x over previous
.LBB0_446:
	s_or_b64 exec, exec, s[0:1]
	s_mov_b64 s[2:3], s[72:73]
	v_readlane_b32 s12, v254, 35
	v_readlane_b32 s0, v254, 60
	s_and_b64 vcc, exec, s[58:59]
	s_waitcnt lgkmcnt(0)
	s_barrier
	v_readlane_b32 s1, v254, 61
	s_cbranch_vccz .LBB0_494
	s_load_dwordx2 s[0:1], s[2:3], 0x88
	s_load_dwordx8 s[4:11], s[2:3], 0x48
	s_nop 0
	s_load_dwordx2 s[2:3], s[2:3], 0x68
	s_mov_b32 s39, s70
	s_waitcnt lgkmcnt(0)
	s_add_u32 s14, s0, 0xc000000
	s_addc_u32 s15, s1, 0
	s_add_u32 s33, s0, 0xe000000
	s_addc_u32 s36, s1, 0
	s_lshl_b32 s16, s12, 12
	s_ashr_i32 s17, s16, 31
	s_lshl_b64 s[16:17], s[16:17], 2
	s_add_u32 s16, s4, s16
	s_addc_u32 s17, s5, s17
	s_lshl_b32 s4, s12, 10
	s_ashr_i32 s5, s4, 31
	s_lshl_b64 s[4:5], s[4:5], 2
	s_add_u32 s18, s6, s4
	s_addc_u32 s19, s7, s5
	s_add_u32 s37, s0, 0x18200000
	s_addc_u32 s38, s1, 0
	s_lshl_b32 s4, s12, 7
	s_ashr_i32 s5, s4, 31
	s_lshl_b64 s[4:5], s[4:5], 2
	s_add_u32 s20, s2, s4
	s_addc_u32 s21, s3, s5
	s_add_u32 s22, s0, 0x12000000
	s_addc_u32 s23, s1, 0
	s_add_u32 s24, s0, 0x4000000
	s_addc_u32 s25, s1, 0
	s_lshl_b32 s2, s12, 3
	s_ashr_i32 s3, s2, 31
	s_lshl_b64 s[2:3], s[2:3], 2
	s_add_u32 s26, s10, s2
	s_addc_u32 s27, s11, s3
	s_add_u32 s28, s8, s2
	s_addc_u32 s29, s9, s3
	s_add_u32 s30, s0, 0x18000000
	s_addc_u32 s31, s1, 0
	s_mov_b32 s56, s39
	s_ashr_i32 s98, s56, 10
	s_ashr_i32 s99, s98, 31
	s_lshl_b64 s[98:99], s[98:99], 13
	s_and_b32 s100, s56, 0x7f
	s_lshl_b32 s90, s100, 6
	s_or_b32 s98, s98, s90
	s_bfe_u32 s57, s56, 0x30007
	v_readfirstlane_b32 s101, v194
	v_lshrrev_b32_e32 v209, 3, v194
	v_and_b32_e32 v210, 7, v194
	v_lshlrev_b32_e32 v211, 4, v210
	v_lshl_or_b32 v190, v209, 15, v211
	v_lshlrev_b32_e32 v191, 4, v194
	v_lshl_or_b32 v192, v209, 11, v211
	v_add_u32_e32 v193, 0x1000, v192
	v_lshlrev_b32_e32 v208, 5, v210
	s_lshl_b32 s90, s57, 7
	s_or_b32 s90, s90, 0x400
	s_lshl_b64 s[52:53], s[98:99], 1
	s_add_u32 s52, s33, s52
	s_addc_u32 s53, s36, s53
	s_lshl_b32 s91, s90, 15
	s_add_u32 s52, s52, s91
	s_addc_u32 s53, s53, 0
	s_add_u32 s54, s52, 0x200000
	s_addc_u32 s55, s53, 0
	global_load_dwordx4 v[44:47], v190, s[52:53]
	global_load_dwordx4 v[48:51], v190, s[54:55]
	s_mul_i32 s92, s56, 0x4080
	s_mul_hi_i32 s93, s56, 0x4080
	s_add_u32 s92, s37, s92
	s_addc_u32 s93, s38, s93
	global_load_dwordx4 v[52:55], v191, s[92:93]
	s_add_u32 s94, s92, 0x2000
	s_addc_u32 s95, s93, 0
	global_load_dwordx4 v[56:59], v191, s[94:95]
	s_add_u32 s94, s92, 0x4000
	s_addc_u32 s95, s93, 0
	v_cmp_gt_u32_e32 vcc, 8, v194
	s_and_saveexec_b64 s[96:97], vcc
	global_load_dwordx4 v[60:63], v191, s[94:95]
	s_mov_b64 exec, s[96:97]
	s_lshl_b32 s91, s57, 8
	s_add_u32 s94, s18, s91
	s_addc_u32 s95, s19, 0
	global_load_dwordx4 v[64:67], v208, s[94:95]
	global_load_dwordx4 v[68:71], v208, s[94:95] offset:16
	global_load_dwordx4 v[72:75], v208, s[94:95] offset:2048
	global_load_dwordx4 v[76:79], v208, s[94:95] offset:2064
	s_add_u32 s94, s16, s91
	s_addc_u32 s95, s17, 0
	global_load_dwordx4 v[84:87], v208, s[94:95]
	global_load_dwordx4 v[88:91], v208, s[94:95] offset:16
	global_load_dwordx4 v[132:135], v208, s[94:95] offset:2048
	global_load_dwordx4 v[136:139], v208, s[94:95] offset:2064
	s_add_u32 s94, s94, 0x1000
	s_addc_u32 s95, s95, 0
	global_load_dwordx4 v[96:99], v208, s[94:95]
	global_load_dwordx4 v[100:103], v208, s[94:95] offset:16
	global_load_dwordx4 v[144:147], v208, s[94:95] offset:2048
	global_load_dwordx4 v[148:151], v208, s[94:95] offset:2064
	s_add_u32 s94, s94, 0x1000
	s_addc_u32 s95, s95, 0
	global_load_dwordx4 v[108:111], v208, s[94:95]
	global_load_dwordx4 v[112:115], v208, s[94:95] offset:16
	global_load_dwordx4 v[156:159], v208, s[94:95] offset:2048
	global_load_dwordx4 v[160:163], v208, s[94:95] offset:2064
	s_add_u32 s94, s94, 0x1000
	s_addc_u32 s95, s95, 0
	global_load_dwordx4 v[120:123], v208, s[94:95]
	global_load_dwordx4 v[124:127], v208, s[94:95] offset:16
	global_load_dwordx4 v[182:185], v208, s[94:95] offset:2048
	global_load_dwordx4 v[186:189], v208, s[94:95] offset:2064
	s_sub_u32 s92, s98, 3
	s_subb_u32 s93, s99, 0
	s_lshl_b64 s[92:93], s[92:93], 11
	s_add_u32 s92, s14, s92
	s_addc_u32 s93, s15, s93
	s_lshl_b32 s91, s57, 7
	s_add_u32 s92, s92, s91
	s_addc_u32 s93, s93, 0
	s_cmp_lg_u32 s100, 0
	s_cselect_b64 s[54:55], -1, 0
	v_cmp_lt_u32_e32 vcc, 2, v209
	s_or_b64 s[46:47], s[54:55], vcc
	v_cmp_lt_u32_e32 vcc, 1, v209
	s_or_b64 s[48:49], s[54:55], vcc
	v_cmp_lt_u32_e32 vcc, 0, v209
	s_or_b64 s[50:51], s[54:55], vcc
	s_mov_b64 s[96:97], exec
	s_and_b64 exec, s[96:97], s[46:47]
	global_load_dwordx4 v[80:83], v192, s[92:93]
	global_load_dwordx4 v[128:131], v192, s[92:93] offset:1024
	s_and_b64 exec, s[96:97], s[48:49]
	global_load_dwordx4 v[92:95], v192, s[92:93] offset:2048
	global_load_dwordx4 v[140:143], v192, s[92:93] offset:3072
	s_and_b64 exec, s[96:97], s[50:51]
	global_load_dwordx4 v[104:107], v193, s[92:93]
	global_load_dwordx4 v[152:155], v193, s[92:93] offset:1024
	s_mov_b64 exec, s[96:97]
	global_load_dwordx4 v[116:119], v193, s[92:93] offset:2048
	global_load_dwordx4 v[178:181], v193, s[92:93] offset:3072
	s_lshr_b32 s90, s101, 6
	s_lshl_b32 s90, s90, 3
	s_add_u32 s90, s98, s90
	s_addc_u32 s91, s99, 0
	s_lshl_b64 s[90:91], s[90:91], 11
	s_add_u32 s90, s22, s90
	s_addc_u32 s91, s23, s91
	s_lshl_b32 s92, s57, 8
	v_and_b32_e32 v232, 63, v194
	v_lshlrev_b32_e32 v233, 3, v232
	v_lshl_or_b32 v232, v232, 2, s92
	global_load_dword v224, v232, s[90:91]
	global_load_dword v225, v232, s[90:91] offset:2048
	s_add_u32 s90, s90, 0x1000
	s_addc_u32 s91, s91, 0
	global_load_dword v226, v232, s[90:91]
	global_load_dword v227, v232, s[90:91] offset:2048
	s_add_u32 s90, s90, 0x1000
	s_addc_u32 s91, s91, 0
	global_load_dword v228, v232, s[90:91]
	global_load_dword v229, v232, s[90:91] offset:2048
	s_add_u32 s90, s90, 0x1000
	s_addc_u32 s91, s91, 0
	global_load_dword v230, v232, s[90:91]
	global_load_dword v231, v232, s[90:91] offset:2048
	global_load_dwordx2 v[234:235], v233, s[20:21]
	s_cmp_gt_u32 s101, 63
	s_cbranch_scc1 .Lm3_pf_nog_a
	v_and_b32_e32 v217, 63, v194
	v_or_b32_e32 v218, s98, v217
	v_mov_b32_e32 v219, s99
	v_lshlrev_b64 v[218:219], 6, v[218:219]
	v_lshl_add_u64 v[218:219], s[30:31], 0, v[218:219]
	s_lshl_b32 s90, s57, 2
	s_mov_b32 s91, 0
	v_lshl_add_u64 v[218:219], v[218:219], 0, s[90:91]
	v_mov_b32_e32 v220, s90
	global_load_dword v212, v[218:219], off offset:32
	global_load_dword v213, v220, s[26:27]
	global_load_dword v214, v[218:219], off
	global_load_dword v215, v220, s[28:29]
	s_lshl_b32 s90, s56, 4
	s_add_u32 s90, s0, s90
	s_addc_u32 s91, s1, 0
	v_mov_b32_e32 v221, 0x18100000
	global_load_dword v216, v221, s[90:91] offset:8
.Lm3_pf_nog_a:
	s_waitcnt vmcnt(0)
	s_branch .LBB0_449
.LBB0_448:
	s_or_b64 exec, exec, s[2:3]
	v_bfe_u32 v3, v1, 16, 1
	s_movk_i32 s2, 0x7fff
	v_lshlrev_b32_e32 v2, 3, v4
	v_add3_u32 v1, v1, v3, s2
	ds_write_b16_d16_hi v0, v1 offset:60336
	v_mul_u32_u24_e32 v0, 0x90, v9
	v_lshlrev_b32_e32 v1, 1, v2
	s_waitcnt lgkmcnt(0)
	s_barrier
	v_add3_u32 v12, 0, v0, v1
	ds_read_b128 v[14:17], v10 offset:59904
	ds_read_b128 v[0:3], v12 offset:36864
	ds_read_b128 v[18:21], v10 offset:59968
	ds_read_b128 v[4:7], v12 offset:36928
	s_waitcnt lgkmcnt(2)
	v_mfma_f32_16x16x32_bf16 v[0:3], v[14:17], v[0:3], 0
	s_lshl_b32 s2, s4, 2
	s_add_i32 s2, s2, 0
	s_add_i32 s2, s2, 0x19200
	s_waitcnt lgkmcnt(0)
	v_mfma_f32_16x16x32_bf16 v[24:27], v[18:21], v[4:7], v[0:3]
	ds_read_b128 v[28:31], v10
	s_nop 1
	ds_read_b128 v[0:3], v12 offset:57600
	ds_read_b128 v[32:35], v10 offset:64
	ds_read_b128 v[4:7], v12 offset:57664
	s_ashr_i32 s3, s40, 6
	s_waitcnt lgkmcnt(2)
	v_mfma_f32_16x16x32_bf16 v[0:3], v[28:31], v[0:3], 0
	v_readlane_b32 s7, v254, 34
	s_waitcnt lgkmcnt(0)
	v_mfma_f32_16x16x32_bf16 v[36:39], v[32:35], v[4:7], v[0:3]
	s_nop 4
	v_and_b32_e32 v0, 48, v23
	v_add_u32_e32 v4, s2, v0
	v_and_or_b32 v0, v201, 64, v0
	v_lshlrev_b32_e32 v12, 2, v0
	ds_read_b128 v[0:3], v4 offset:512
	ds_read_b128 v[4:7], v4 offset:768
	s_lshl_b32 s2, s3, 4
	s_and_b32 s6, s2, 0xffffffc0
	v_or_b32_e32 v40, s6, v9
	s_waitcnt lgkmcnt(1)
	v_fma_f32 v13, v36, v0, v24
	v_fma_f32 v23, v37, v1, v25
	v_fma_f32 v24, v38, v2, v26
	v_fmac_f32_e32 v27, v39, v3
	v_mad_u64_u32 v[36:37], s[4:5], v40, s84, v[8:9]
	ds_bpermute_b32 v38, v12, v24
	ds_bpermute_b32 v39, v12, v27
	ds_read_b128 v[24:27], v36 offset:18432
	s_waitcnt lgkmcnt(0)
	v_mfma_f32_16x16x32_bf16 v[14:17], v[14:17], v[24:27], 0
	ds_read_b128 v[24:27], v36 offset:18496
	ds_bpermute_b32 v13, v12, v13
	v_max_f32_e32 v4, v4, v4
	s_waitcnt lgkmcnt(1)
	v_mfma_f32_16x16x32_bf16 v[14:17], v[18:21], v[24:27], v[14:17]
	ds_read_b128 v[18:21], v36 offset:39168
	ds_read_b128 v[24:27], v36 offset:39232
	s_waitcnt lgkmcnt(2)
	v_max_f32_e64 v13, |v13|, |v13|
	s_waitcnt lgkmcnt(1)
	v_mfma_f32_16x16x32_bf16 v[18:21], v[28:31], v[18:21], 0
	v_max_f32_e32 v4, v13, v4
	ds_bpermute_b32 v23, v12, v23
	v_lshl_add_u32 v12, v9, 2, s7
	s_waitcnt lgkmcnt(1)
	v_mfma_f32_16x16x32_bf16 v[18:21], v[32:35], v[24:27], v[18:21]
	v_lshl_add_u32 v24, s6, 2, v12
	s_movk_i32 s6, 0x210
	v_mad_u32_u24 v36, v11, s6, v24
	v_max_f32_e32 v5, v5, v5
	v_max_f32_e32 v6, v6, v6
	s_nop 2
	v_fma_f32 v14, v0, v18, v14
	v_div_scale_f32 v13, s[4:5], v4, v4, v14
	v_rcp_f32_e32 v18, v13
	v_max_f32_e32 v7, v7, v7
	v_fmac_f32_e32 v17, v3, v21
	s_or_b32 s2, s2, 48
	v_fma_f32 v25, -v13, v18, 1.0
	v_fmac_f32_e32 v18, v25, v18
	v_div_scale_f32 v25, vcc, v14, v4, v14
	v_mul_f32_e32 v26, v25, v18
	v_fma_f32 v27, -v13, v26, v25
	v_fmac_f32_e32 v26, v27, v18
	v_fma_f32 v13, -v13, v26, v25
	v_div_fmas_f32 v13, v13, v18, v26
	v_div_fixup_f32 v13, v13, v4, v14
	s_waitcnt lgkmcnt(0)
	v_max_f32_e64 v14, |v23|, |v23|
	ds_write_b32 v36, v13
	v_fma_f32 v13, v1, v19, v15
	v_max_f32_e32 v5, v14, v5
	v_div_scale_f32 v14, s[4:5], v5, v5, v13
	v_rcp_f32_e32 v15, v14
	s_nop 0
	v_fma_f32 v18, -v14, v15, 1.0
	v_fmac_f32_e32 v15, v18, v15
	v_div_scale_f32 v18, vcc, v13, v5, v13
	v_mul_f32_e32 v19, v18, v15
	v_fma_f32 v23, -v14, v19, v18
	v_fmac_f32_e32 v19, v23, v15
	v_fma_f32 v14, -v14, v19, v18
	v_div_fmas_f32 v14, v14, v15, v19
	v_div_fixup_f32 v14, v14, v5, v13
	v_mad_u32_u24 v13, v11, s6, s6
	v_add_u32_e32 v23, v24, v13
	v_max_f32_e64 v15, |v38|, |v38|
	ds_write_b32 v23, v14
	v_fma_f32 v14, v2, v20, v16
	v_max_f32_e32 v6, v15, v6
	v_div_scale_f32 v15, s[4:5], v6, v6, v14
	v_rcp_f32_e32 v16, v15
	s_nop 0
	v_fma_f32 v18, -v15, v16, 1.0
	v_fmac_f32_e32 v16, v18, v16
	v_div_scale_f32 v18, vcc, v14, v6, v14
	v_mul_f32_e32 v19, v18, v16
	v_fma_f32 v20, -v15, v19, v18
	v_fmac_f32_e32 v19, v20, v16
	v_fma_f32 v15, -v15, v19, v18
	v_div_fmas_f32 v15, v15, v16, v19
	v_div_fixup_f32 v15, v15, v6, v14
	v_mov_b32_e32 v14, 0x420
	v_mad_u32_u24 v14, v11, s6, v14
	v_add_u32_e32 v37, v24, v14
	ds_write_b32 v37, v15
	v_max_f32_e64 v15, |v39|, |v39|
	v_max_f32_e32 v7, v15, v7
	v_div_scale_f32 v15, s[4:5], v7, v7, v17
	v_rcp_f32_e32 v16, v15
	s_nop 0
	v_fma_f32 v18, -v15, v16, 1.0
	v_fmac_f32_e32 v16, v18, v16
	v_div_scale_f32 v18, vcc, v17, v7, v17
	v_mul_f32_e32 v19, v18, v16
	v_fma_f32 v20, -v15, v19, v18
	v_fmac_f32_e32 v19, v20, v16
	v_fma_f32 v15, -v15, v19, v18
	v_div_fmas_f32 v15, v15, v16, v19
	v_div_fixup_f32 v16, v15, v7, v17
	v_mad_u32_u24 v15, v11, s6, v206
	v_add_u32_e32 v38, v24, v15
	ds_write_b32 v38, v16
	v_or_b32_e32 v16, 16, v40
	v_mad_u64_u32 v[20:21], s[4:5], v16, s84, v[8:9]
	ds_read_b128 v[16:19], v10 offset:59904
	ds_read_b128 v[24:27], v20 offset:18432
	s_waitcnt lgkmcnt(0)
	v_mfma_f32_16x16x32_bf16 v[16:19], v[16:19], v[24:27], 0
	ds_read_b128 v[24:27], v10 offset:59968
	ds_read_b128 v[28:31], v20 offset:18496
	s_waitcnt lgkmcnt(0)
	v_mfma_f32_16x16x32_bf16 v[16:19], v[24:27], v[28:31], v[16:19]
	ds_read_b128 v[24:27], v10
	ds_read_b128 v[28:31], v20 offset:39168
	s_waitcnt lgkmcnt(0)
	v_mfma_f32_16x16x32_bf16 v[24:27], v[24:27], v[28:31], 0
	ds_read_b128 v[28:31], v10 offset:64
	ds_read_b128 v[32:35], v20 offset:39232
	s_waitcnt lgkmcnt(0)
	v_mfma_f32_16x16x32_bf16 v[24:27], v[28:31], v[32:35], v[24:27]
	s_nop 7
	v_fma_f32 v16, v0, v24, v16
	v_div_scale_f32 v20, s[4:5], v4, v4, v16
	v_rcp_f32_e32 v21, v20
	v_fmac_f32_e32 v19, v3, v27
	v_fma_f32 v24, -v20, v21, 1.0
	v_fmac_f32_e32 v21, v24, v21
	v_div_scale_f32 v24, vcc, v16, v4, v16
	v_mul_f32_e32 v28, v24, v21
	v_fma_f32 v29, -v20, v28, v24
	v_fmac_f32_e32 v28, v29, v21
	v_fma_f32 v20, -v20, v28, v24
	v_div_fmas_f32 v20, v20, v21, v28
	v_div_fixup_f32 v16, v20, v4, v16
	ds_write_b32 v36, v16 offset:64
	v_fma_f32 v16, v1, v25, v17
	v_div_scale_f32 v17, s[4:5], v5, v5, v16
	v_rcp_f32_e32 v20, v17
	s_nop 0
	v_fma_f32 v21, -v17, v20, 1.0
	v_fmac_f32_e32 v20, v21, v20
	v_div_scale_f32 v21, vcc, v16, v5, v16
	v_mul_f32_e32 v24, v21, v20
	v_fma_f32 v25, -v17, v24, v21
	v_fmac_f32_e32 v24, v25, v20
	v_fma_f32 v17, -v17, v24, v21
	v_div_fmas_f32 v17, v17, v20, v24
	v_div_fixup_f32 v16, v17, v5, v16
	ds_write_b32 v23, v16 offset:64
	v_fma_f32 v16, v2, v26, v18
	v_div_scale_f32 v17, s[4:5], v6, v6, v16
	v_rcp_f32_e32 v18, v17
	s_nop 0
	v_fma_f32 v20, -v17, v18, 1.0
	v_fmac_f32_e32 v18, v20, v18
	v_div_scale_f32 v20, vcc, v16, v6, v16
	v_mul_f32_e32 v21, v20, v18
	v_fma_f32 v24, -v17, v21, v20
	v_fmac_f32_e32 v21, v24, v18
	v_fma_f32 v17, -v17, v21, v20
	v_div_fmas_f32 v17, v17, v18, v21
	v_div_fixup_f32 v16, v17, v6, v16
	ds_write_b32 v37, v16 offset:64
	v_div_scale_f32 v16, s[4:5], v7, v7, v19
	v_rcp_f32_e32 v17, v16
	s_nop 0
	v_fma_f32 v18, -v16, v17, 1.0
	v_fmac_f32_e32 v17, v18, v17
	v_div_scale_f32 v18, vcc, v19, v7, v19
	v_mul_f32_e32 v20, v18, v17
	v_fma_f32 v21, -v16, v20, v18
	v_fmac_f32_e32 v20, v21, v17
	v_fma_f32 v16, -v16, v20, v18
	v_div_fmas_f32 v16, v16, v17, v20
	v_div_fixup_f32 v16, v16, v7, v19
	ds_write_b32 v38, v16 offset:64
	v_or_b32_e32 v16, 32, v40
	v_mad_u64_u32 v[20:21], s[4:5], v16, s84, v[8:9]
	ds_read_b128 v[16:19], v10 offset:59904
	ds_read_b128 v[24:27], v20 offset:18432
	s_waitcnt lgkmcnt(0)
	v_mfma_f32_16x16x32_bf16 v[16:19], v[16:19], v[24:27], 0
	ds_read_b128 v[24:27], v10 offset:59968
	ds_read_b128 v[28:31], v20 offset:18496
	v_or_b32_e32 v9, s2, v9
	v_mad_u64_u32 v[8:9], s[4:5], v9, s84, v[8:9]
	s_waitcnt lgkmcnt(0)
	v_mfma_f32_16x16x32_bf16 v[16:19], v[24:27], v[28:31], v[16:19]
	ds_read_b128 v[24:27], v10
	ds_read_b128 v[28:31], v20 offset:39168
	s_waitcnt lgkmcnt(0)
	v_mfma_f32_16x16x32_bf16 v[24:27], v[24:27], v[28:31], 0
	ds_read_b128 v[28:31], v10 offset:64
	ds_read_b128 v[32:35], v20 offset:39232
	s_waitcnt lgkmcnt(0)
	v_mfma_f32_16x16x32_bf16 v[24:27], v[28:31], v[32:35], v[24:27]
	s_nop 7
	v_fma_f32 v16, v0, v24, v16
	v_div_scale_f32 v20, s[4:5], v4, v4, v16
	v_rcp_f32_e32 v21, v20
	v_fmac_f32_e32 v19, v3, v27
	v_fma_f32 v24, -v20, v21, 1.0
	v_fmac_f32_e32 v21, v24, v21
	v_div_scale_f32 v24, vcc, v16, v4, v16
	v_mul_f32_e32 v28, v24, v21
	v_fma_f32 v29, -v20, v28, v24
	v_fmac_f32_e32 v28, v29, v21
	v_fma_f32 v20, -v20, v28, v24
	v_div_fmas_f32 v20, v20, v21, v28
	v_div_fixup_f32 v16, v20, v4, v16
	ds_write_b32 v36, v16 offset:128
	v_fma_f32 v16, v1, v25, v17
	v_div_scale_f32 v17, s[4:5], v5, v5, v16
	v_rcp_f32_e32 v20, v17
	s_nop 0
	v_fma_f32 v21, -v17, v20, 1.0
	v_fmac_f32_e32 v20, v21, v20
	v_div_scale_f32 v21, vcc, v16, v5, v16
	v_mul_f32_e32 v24, v21, v20
	v_fma_f32 v25, -v17, v24, v21
	v_fmac_f32_e32 v24, v25, v20
	v_fma_f32 v17, -v17, v24, v21
	v_div_fmas_f32 v17, v17, v20, v24
	v_div_fixup_f32 v16, v17, v5, v16
	ds_write_b32 v23, v16 offset:128
	v_fma_f32 v16, v2, v26, v18
	v_div_scale_f32 v17, s[4:5], v6, v6, v16
	v_rcp_f32_e32 v18, v17
	s_nop 0
	v_fma_f32 v20, -v17, v18, 1.0
	v_fmac_f32_e32 v18, v20, v18
	v_div_scale_f32 v20, vcc, v16, v6, v16
	v_mul_f32_e32 v21, v20, v18
	v_fma_f32 v23, -v17, v21, v20
	v_fmac_f32_e32 v21, v23, v18
	v_fma_f32 v17, -v17, v21, v20
	v_div_fmas_f32 v17, v17, v18, v21
	v_div_fixup_f32 v16, v17, v6, v16
	ds_write_b32 v37, v16 offset:128
	v_div_scale_f32 v16, s[4:5], v7, v7, v19
	v_rcp_f32_e32 v17, v16
	s_nop 0
	v_fma_f32 v18, -v16, v17, 1.0
	v_fmac_f32_e32 v17, v18, v17
	v_div_scale_f32 v18, vcc, v19, v7, v19
	v_mul_f32_e32 v20, v18, v17
	v_fma_f32 v21, -v16, v20, v18
	v_fmac_f32_e32 v20, v21, v17
	v_fma_f32 v16, -v16, v20, v18
	v_div_fmas_f32 v16, v16, v17, v20
	v_div_fixup_f32 v16, v16, v7, v19
	ds_write_b32 v38, v16 offset:128
	ds_read_b128 v[16:19], v10 offset:59904
	ds_read_b128 v[24:27], v8 offset:18432
	s_waitcnt lgkmcnt(0)
	v_mfma_f32_16x16x32_bf16 v[16:19], v[16:19], v[24:27], 0
	ds_read_b128 v[24:27], v10 offset:59968
	ds_read_b128 v[28:31], v8 offset:18496
	s_waitcnt lgkmcnt(0)
	v_mfma_f32_16x16x32_bf16 v[16:19], v[24:27], v[28:31], v[16:19]
	ds_read_b128 v[24:27], v10
	ds_read_b128 v[28:31], v8 offset:39168
	s_waitcnt lgkmcnt(0)
	v_mfma_f32_16x16x32_bf16 v[24:27], v[24:27], v[28:31], 0
	ds_read_b128 v[28:31], v10 offset:64
	ds_read_b128 v[32:35], v8 offset:39232
	v_lshl_add_u32 v8, s2, 2, v12
	s_lshl_b32 s2, s3, 3
	s_waitcnt lgkmcnt(0)
	v_mfma_f32_16x16x32_bf16 v[24:27], v[28:31], v[32:35], v[24:27]
	s_mulk_i32 s3, 0x1080
	s_nop 6
	v_fma_f32 v0, v0, v24, v16
	v_div_scale_f32 v9, s[4:5], v4, v4, v0
	v_rcp_f32_e32 v10, v9
	v_fmac_f32_e32 v19, v3, v27
	v_fma_f32 v12, -v9, v10, 1.0
	v_fmac_f32_e32 v10, v12, v10
	v_div_scale_f32 v12, vcc, v0, v4, v0
	v_mul_f32_e32 v16, v12, v10
	v_fma_f32 v20, -v9, v16, v12
	v_fmac_f32_e32 v16, v20, v10
	v_fma_f32 v9, -v9, v16, v12
	v_div_fmas_f32 v9, v9, v10, v16
	v_div_fixup_f32 v0, v9, v4, v0
	v_mad_u32_u24 v4, v11, s6, v8
	ds_write_b32 v4, v0
	v_fma_f32 v0, v1, v25, v17
	v_div_scale_f32 v1, s[4:5], v5, v5, v0
	v_rcp_f32_e32 v4, v1
	s_nop 0
	v_fma_f32 v9, -v1, v4, 1.0
	v_fmac_f32_e32 v4, v9, v4
	v_div_scale_f32 v9, vcc, v0, v5, v0
	v_mul_f32_e32 v10, v9, v4
	v_fma_f32 v11, -v1, v10, v9
	v_fmac_f32_e32 v10, v11, v4
	v_fma_f32 v1, -v1, v10, v9
	v_div_fmas_f32 v1, v1, v4, v10
	v_div_fixup_f32 v0, v1, v5, v0
	v_add_u32_e32 v1, v8, v13
	ds_write_b32 v1, v0
	v_fma_f32 v0, v2, v26, v18
	v_div_scale_f32 v1, s[4:5], v6, v6, v0
	v_rcp_f32_e32 v2, v1
	s_nop 0
	v_fma_f32 v4, -v1, v2, 1.0
	v_fmac_f32_e32 v2, v4, v2
	v_div_scale_f32 v4, vcc, v0, v6, v0
	v_mul_f32_e32 v5, v4, v2
	v_fma_f32 v9, -v1, v5, v4
	v_fmac_f32_e32 v5, v9, v2
	v_fma_f32 v1, -v1, v5, v4
	v_div_fmas_f32 v1, v1, v2, v5
	v_div_fixup_f32 v0, v1, v6, v0
	v_add_u32_e32 v1, v8, v14
	ds_write_b32 v1, v0
	v_div_scale_f32 v0, s[4:5], v7, v7, v19
	v_rcp_f32_e32 v1, v0
	s_nop 0
	v_fma_f32 v2, -v0, v1, 1.0
	v_fmac_f32_e32 v1, v2, v1
	v_div_scale_f32 v2, vcc, v19, v7, v19
	v_mul_f32_e32 v3, v2, v1
	v_fma_f32 v4, -v0, v3, v2
	v_fmac_f32_e32 v3, v4, v1
	v_fma_f32 v0, -v0, v3, v2
	v_lshlrev_b32_e32 v2, 3, v22
	v_div_fmas_f32 v0, v0, v1, v3
	v_add_u32_e32 v10, s7, v2
	v_div_fixup_f32 v0, v0, v7, v19
	v_add_u32_e32 v1, v8, v15
	v_add_u32_e32 v6, s3, v10
	ds_write_b32 v1, v0
	s_waitcnt lgkmcnt(0)
	s_barrier
	s_add_u32 s4, s34, s2
	s_addc_u32 s5, s35, 0
	s_lshl_b64 s[4:5], s[4:5], 11
	s_lshl_b32 s3, s12, 1
	v_lshl_or_b32 v3, v22, 2, s3
	ds_read_b64 v[8:9], v6
	ds_read_b64 v[10:11], v6 offset:528
	ds_read_b64 v[12:13], v6 offset:1056
	ds_read_b64 v[14:15], v6 offset:1584
	ds_read_b64 v[16:17], v6 offset:2112
	ds_read_b64 v[18:19], v6 offset:2640
	ds_read_b64 v[20:21], v6 offset:3168
	ds_read_b64 v[22:23], v6 offset:3696
	s_add_u32 s98, s24, s4
	s_addc_u32 s99, s25, s5
	v_lshlrev_b32_e32 v164, 2, v201
	v_xor_b32_e32 v165, 4, v164
	v_xor_b32_e32 v166, 8, v164
	v_xor_b32_e32 v167, 16, v164
	v_xor_b32_e32 v168, 32, v164
	v_xor_b32_e32 v169, 64, v164
	v_xor_b32_e32 v170, 0x80, v164
	s_waitcnt lgkmcnt(0)
	v_pk_mul_f32 v[196:197], v[8:9], v[8:9]
	v_add_f32_e32 v24, v196, v197
	v_pk_mul_f32 v[196:197], v[10:11], v[10:11]
	v_add_f32_e32 v25, v196, v197
	v_pk_mul_f32 v[196:197], v[12:13], v[12:13]
	v_add_f32_e32 v26, v196, v197
	v_pk_mul_f32 v[196:197], v[14:15], v[14:15]
	v_add_f32_e32 v27, v196, v197
	v_pk_mul_f32 v[196:197], v[16:17], v[16:17]
	v_add_f32_e32 v28, v196, v197
	v_pk_mul_f32 v[196:197], v[18:19], v[18:19]
	v_add_f32_e32 v29, v196, v197
	v_pk_mul_f32 v[196:197], v[20:21], v[20:21]
	v_add_f32_e32 v30, v196, v197
	v_pk_mul_f32 v[196:197], v[22:23], v[22:23]
	v_add_f32_e32 v31, v196, v197
	ds_bpermute_b32 v32, v165, v24
	ds_bpermute_b32 v33, v165, v25
	ds_bpermute_b32 v34, v165, v26
	ds_bpermute_b32 v35, v165, v27
	ds_bpermute_b32 v36, v165, v28
	ds_bpermute_b32 v37, v165, v29
	ds_bpermute_b32 v38, v165, v30
	ds_bpermute_b32 v39, v165, v31
	s_waitcnt lgkmcnt(0)
	v_add_f32_e32 v24, v24, v32
	v_add_f32_e32 v25, v25, v33
	v_add_f32_e32 v26, v26, v34
	v_add_f32_e32 v27, v27, v35
	v_add_f32_e32 v28, v28, v36
	v_add_f32_e32 v29, v29, v37
	v_add_f32_e32 v30, v30, v38
	v_add_f32_e32 v31, v31, v39
	ds_bpermute_b32 v32, v166, v24
	ds_bpermute_b32 v33, v166, v25
	ds_bpermute_b32 v34, v166, v26
	ds_bpermute_b32 v35, v166, v27
	ds_bpermute_b32 v36, v166, v28
	ds_bpermute_b32 v37, v166, v29
	ds_bpermute_b32 v38, v166, v30
	ds_bpermute_b32 v39, v166, v31
	s_waitcnt lgkmcnt(0)
	v_add_f32_e32 v24, v24, v32
	v_add_f32_e32 v25, v25, v33
	v_add_f32_e32 v26, v26, v34
	v_add_f32_e32 v27, v27, v35
	v_add_f32_e32 v28, v28, v36
	v_add_f32_e32 v29, v29, v37
	v_add_f32_e32 v30, v30, v38
	v_add_f32_e32 v31, v31, v39
	ds_bpermute_b32 v32, v167, v24
	ds_bpermute_b32 v33, v167, v25
	ds_bpermute_b32 v34, v167, v26
	ds_bpermute_b32 v35, v167, v27
	ds_bpermute_b32 v36, v167, v28
	ds_bpermute_b32 v37, v167, v29
	ds_bpermute_b32 v38, v167, v30
	ds_bpermute_b32 v39, v167, v31
	s_waitcnt lgkmcnt(0)
	v_add_f32_e32 v24, v24, v32
	v_add_f32_e32 v25, v25, v33
	v_add_f32_e32 v26, v26, v34
	v_add_f32_e32 v27, v27, v35
	v_add_f32_e32 v28, v28, v36
	v_add_f32_e32 v29, v29, v37
	v_add_f32_e32 v30, v30, v38
	v_add_f32_e32 v31, v31, v39
	ds_bpermute_b32 v32, v168, v24
	ds_bpermute_b32 v33, v168, v25
	ds_bpermute_b32 v34, v168, v26
	ds_bpermute_b32 v35, v168, v27
	ds_bpermute_b32 v36, v168, v28
	ds_bpermute_b32 v37, v168, v29
	ds_bpermute_b32 v38, v168, v30
	ds_bpermute_b32 v39, v168, v31
	s_waitcnt lgkmcnt(0)
	v_add_f32_e32 v24, v24, v32
	v_add_f32_e32 v25, v25, v33
	v_add_f32_e32 v26, v26, v34
	v_add_f32_e32 v27, v27, v35
	v_add_f32_e32 v28, v28, v36
	v_add_f32_e32 v29, v29, v37
	v_add_f32_e32 v30, v30, v38
	v_add_f32_e32 v31, v31, v39
	ds_bpermute_b32 v32, v169, v24
	ds_bpermute_b32 v33, v169, v25
	ds_bpermute_b32 v34, v169, v26
	ds_bpermute_b32 v35, v169, v27
	ds_bpermute_b32 v36, v169, v28
	ds_bpermute_b32 v37, v169, v29
	ds_bpermute_b32 v38, v169, v30
	ds_bpermute_b32 v39, v169, v31
	s_waitcnt lgkmcnt(0)
	v_add_f32_e32 v24, v24, v32
	v_add_f32_e32 v25, v25, v33
	v_add_f32_e32 v26, v26, v34
	v_add_f32_e32 v27, v27, v35
	v_add_f32_e32 v28, v28, v36
	v_add_f32_e32 v29, v29, v37
	v_add_f32_e32 v30, v30, v38
	v_add_f32_e32 v31, v31, v39
	ds_bpermute_b32 v32, v170, v24
	ds_bpermute_b32 v33, v170, v25
	ds_bpermute_b32 v34, v170, v26
	ds_bpermute_b32 v35, v170, v27
	ds_bpermute_b32 v36, v170, v28
	ds_bpermute_b32 v37, v170, v29
	ds_bpermute_b32 v38, v170, v30
	ds_bpermute_b32 v39, v170, v31
	s_waitcnt lgkmcnt(0)
	v_add_f32_e32 v24, v24, v32
	v_add_f32_e32 v25, v25, v33
	v_add_f32_e32 v26, v26, v34
	v_add_f32_e32 v27, v27, v35
	v_add_f32_e32 v28, v28, v36
	v_add_f32_e32 v29, v29, v37
	v_add_f32_e32 v30, v30, v38
	v_add_f32_e32 v31, v31, v39
	v_fmamk_f32 v24, v24, 0x3c000000, v195
	v_cmp_gt_f32_e32 vcc, s67, v24
	v_mul_f32_e32 v32, 0x4b800000, v24
	s_nop 0
	v_cndmask_b32_e32 v24, v24, v32, vcc
	v_rsq_f32_e32 v24, v24
	s_nop 0
	v_mul_f32_e32 v32, 0x45800000, v24
	v_cndmask_b32_e32 v24, v24, v32, vcc
	v_fmamk_f32 v25, v25, 0x3c000000, v195
	v_cmp_gt_f32_e32 vcc, s67, v25
	v_mul_f32_e32 v33, 0x4b800000, v25
	s_nop 0
	v_cndmask_b32_e32 v25, v25, v33, vcc
	v_rsq_f32_e32 v25, v25
	s_nop 0
	v_mul_f32_e32 v33, 0x45800000, v25
	v_cndmask_b32_e32 v25, v25, v33, vcc
	v_fmamk_f32 v26, v26, 0x3c000000, v195
	v_cmp_gt_f32_e32 vcc, s67, v26
	v_mul_f32_e32 v34, 0x4b800000, v26
	s_nop 0
	v_cndmask_b32_e32 v26, v26, v34, vcc
	v_rsq_f32_e32 v26, v26
	s_nop 0
	v_mul_f32_e32 v34, 0x45800000, v26
	v_cndmask_b32_e32 v26, v26, v34, vcc
	v_fmamk_f32 v27, v27, 0x3c000000, v195
	v_cmp_gt_f32_e32 vcc, s67, v27
	v_mul_f32_e32 v35, 0x4b800000, v27
	s_nop 0
	v_cndmask_b32_e32 v27, v27, v35, vcc
	v_rsq_f32_e32 v27, v27
	s_nop 0
	v_mul_f32_e32 v35, 0x45800000, v27
	v_cndmask_b32_e32 v27, v27, v35, vcc
	v_fmamk_f32 v28, v28, 0x3c000000, v195
	v_cmp_gt_f32_e32 vcc, s67, v28
	v_mul_f32_e32 v36, 0x4b800000, v28
	s_nop 0
	v_cndmask_b32_e32 v28, v28, v36, vcc
	v_rsq_f32_e32 v28, v28
	s_nop 0
	v_mul_f32_e32 v36, 0x45800000, v28
	v_cndmask_b32_e32 v28, v28, v36, vcc
	v_fmamk_f32 v29, v29, 0x3c000000, v195
	v_cmp_gt_f32_e32 vcc, s67, v29
	v_mul_f32_e32 v37, 0x4b800000, v29
	s_nop 0
	v_cndmask_b32_e32 v29, v29, v37, vcc
	v_rsq_f32_e32 v29, v29
	s_nop 0
	v_mul_f32_e32 v37, 0x45800000, v29
	v_cndmask_b32_e32 v29, v29, v37, vcc
	v_fmamk_f32 v30, v30, 0x3c000000, v195
	v_cmp_gt_f32_e32 vcc, s67, v30
	v_mul_f32_e32 v38, 0x4b800000, v30
	s_nop 0
	v_cndmask_b32_e32 v30, v30, v38, vcc
	v_rsq_f32_e32 v30, v30
	s_nop 0
	v_mul_f32_e32 v38, 0x45800000, v30
	v_cndmask_b32_e32 v30, v30, v38, vcc
	v_fmamk_f32 v31, v31, 0x3c000000, v195
	v_cmp_gt_f32_e32 vcc, s67, v31
	v_mul_f32_e32 v39, 0x4b800000, v31
	s_nop 0
	v_cndmask_b32_e32 v31, v31, v39, vcc
	v_rsq_f32_e32 v31, v31
	s_nop 0
	v_mul_f32_e32 v39, 0x45800000, v31
	v_cndmask_b32_e32 v31, v31, v39, vcc
	v_mul_f32_e32 v8, v8, v24
	v_mul_f32_e32 v9, v9, v24
	v_pk_mul_f32 v[8:9], v[244:245], v[8:9]
	v_lshlrev_b32_e32 v32, 16, v236
	v_and_b32_e32 v236, 0xffff0000, v236
	v_mul_f32_e32 v8, v8, v32
	v_mul_f32_e32 v9, v9, v236
	v_cvt_pk_bf16_f32 v32, v8, v9
	global_store_dword v3, v32, s[98:99]
	v_mul_f32_e32 v10, v10, v25
	v_mul_f32_e32 v11, v11, v25
	v_pk_mul_f32 v[10:11], v[244:245], v[10:11]
	v_lshlrev_b32_e32 v33, 16, v237
	v_and_b32_e32 v237, 0xffff0000, v237
	v_mul_f32_e32 v10, v10, v33
	v_mul_f32_e32 v11, v11, v237
	v_cvt_pk_bf16_f32 v33, v10, v11
	global_store_dword v3, v33, s[98:99] offset:2048
	s_add_u32 s98, s98, 0x1000
	s_addc_u32 s99, s99, 0
	v_mul_f32_e32 v12, v12, v26
	v_mul_f32_e32 v13, v13, v26
	v_pk_mul_f32 v[12:13], v[244:245], v[12:13]
	v_lshlrev_b32_e32 v34, 16, v238
	v_and_b32_e32 v238, 0xffff0000, v238
	v_mul_f32_e32 v12, v12, v34
	v_mul_f32_e32 v13, v13, v238
	v_cvt_pk_bf16_f32 v34, v12, v13
	global_store_dword v3, v34, s[98:99]
	v_mul_f32_e32 v14, v14, v27
	v_mul_f32_e32 v15, v15, v27
	v_pk_mul_f32 v[14:15], v[244:245], v[14:15]
	v_lshlrev_b32_e32 v35, 16, v239
	v_and_b32_e32 v239, 0xffff0000, v239
	v_mul_f32_e32 v14, v14, v35
	v_mul_f32_e32 v15, v15, v239
	v_cvt_pk_bf16_f32 v35, v14, v15
	global_store_dword v3, v35, s[98:99] offset:2048
	s_add_u32 s98, s98, 0x1000
	s_addc_u32 s99, s99, 0
	v_mul_f32_e32 v16, v16, v28
	v_mul_f32_e32 v17, v17, v28
	v_pk_mul_f32 v[16:17], v[244:245], v[16:17]
	v_lshlrev_b32_e32 v36, 16, v240
	v_and_b32_e32 v240, 0xffff0000, v240
	v_mul_f32_e32 v16, v16, v36
	v_mul_f32_e32 v17, v17, v240
	v_cvt_pk_bf16_f32 v36, v16, v17
	global_store_dword v3, v36, s[98:99]
	v_mul_f32_e32 v18, v18, v29
	v_mul_f32_e32 v19, v19, v29
	v_pk_mul_f32 v[18:19], v[244:245], v[18:19]
	v_lshlrev_b32_e32 v37, 16, v241
	v_and_b32_e32 v241, 0xffff0000, v241
	v_mul_f32_e32 v18, v18, v37
	v_mul_f32_e32 v19, v19, v241
	v_cvt_pk_bf16_f32 v37, v18, v19
	global_store_dword v3, v37, s[98:99] offset:2048
	s_add_u32 s98, s98, 0x1000
	s_addc_u32 s99, s99, 0
	v_mul_f32_e32 v20, v20, v30
	v_mul_f32_e32 v21, v21, v30
	v_pk_mul_f32 v[20:21], v[244:245], v[20:21]
	v_lshlrev_b32_e32 v38, 16, v242
	v_and_b32_e32 v242, 0xffff0000, v242
	v_mul_f32_e32 v20, v20, v38
	v_mul_f32_e32 v21, v21, v242
	v_cvt_pk_bf16_f32 v38, v20, v21
	global_store_dword v3, v38, s[98:99]
	v_mul_f32_e32 v22, v22, v31
	v_mul_f32_e32 v23, v23, v31
	v_pk_mul_f32 v[22:23], v[244:245], v[22:23]
	v_lshlrev_b32_e32 v39, 16, v243
	v_and_b32_e32 v243, 0xffff0000, v243
	v_mul_f32_e32 v22, v22, v39
	v_mul_f32_e32 v23, v23, v243
	v_cvt_pk_bf16_f32 v39, v22, v23
	global_store_dword v3, v39, s[98:99] offset:2048
	s_add_i32 s39, s39, s71
	s_cmpk_gt_i32 s39, 0x7ff
	s_barrier
	s_cbranch_scc1 .LBB0_494
.LBB0_449:
	s_ashr_i32 s2, s39, 10
	s_and_b32 s41, s39, 0x7f
	s_ashr_i32 s3, s2, 31
	v_mov_b32_e32 v23, v194
	s_lshl_b64 s[34:35], s[2:3], 13
	s_lshl_b32 s2, s41, 6
	s_bfe_u32 s42, s39, 0x30007
	v_readfirstlane_b32 s40, v23
	s_or_b32 s34, s34, s2
	s_cmp_gt_u32 s40, 63
	v_and_b32_e32 v22, 63, v23
	s_cbranch_scc1 .LBB0_451
	s_mov_b32 s2, 0x3f317218
	s_waitcnt vmcnt(8)
	v_add_f32_e32 v2, v212, v213
	v_add_f32_e32 v1, v214, v215
	v_min_f32_e32 v0, 0, v2
	v_mul_f32_e64 v2, |v2|, s79
	v_exp_f32_e32 v4, v2
	s_nop 0
	v_add_f32_e32 v5, 1.0, v4
	v_add_f32_e32 v2, -1.0, v5
	v_sub_f32_e32 v3, v2, v5
	v_add_f32_e32 v3, 1.0, v3
	v_sub_f32_e32 v2, v4, v2
	v_add_f32_e32 v6, v2, v3
	v_frexp_mant_f32_e32 v2, v5
	v_cmp_gt_f32_e32 vcc, s85, v2
	v_cvt_f64_f32_e32 v[2:3], v5
	v_frexp_exp_i32_f64_e32 v2, v[2:3]
	v_subbrev_co_u32_e32 v2, vcc, 0, v2, vcc
	v_sub_u32_e32 v3, 0, v2
	v_ldexp_f32 v5, v5, v3
	v_ldexp_f32 v3, v6, v3
	v_add_f32_e32 v6, -1.0, v5
	v_add_f32_e32 v7, 1.0, v6
	v_sub_f32_e32 v7, v5, v7
	v_add_f32_e32 v7, v3, v7
	v_add_f32_e32 v8, v6, v7
	v_sub_f32_e32 v6, v8, v6
	v_sub_f32_e32 v6, v7, v6
	v_add_f32_e32 v7, 1.0, v5
	v_add_f32_e32 v9, -1.0, v7
	v_sub_f32_e32 v5, v5, v9
	v_add_f32_e32 v3, v3, v5
	v_add_f32_e32 v5, v7, v3
	v_sub_f32_e32 v7, v5, v7
	v_sub_f32_e32 v3, v3, v7
	v_rcp_f32_e32 v7, v5
	v_cvt_f32_i32_e32 v2, v2
	v_mul_f32_e32 v9, v8, v7
	v_mul_f32_e32 v10, v5, v9
	v_fma_f32 v11, v9, v5, -v10
	v_fmac_f32_e32 v11, v9, v3
	v_add_f32_e32 v12, v10, v11
	v_sub_f32_e32 v13, v8, v12
	v_sub_f32_e32 v8, v8, v13
	v_sub_f32_e32 v10, v12, v10
	v_sub_f32_e32 v8, v8, v12
	v_add_f32_e32 v6, v6, v8
	v_sub_f32_e32 v8, v10, v11
	v_add_f32_e32 v6, v8, v6
	v_add_f32_e32 v8, v13, v6
	v_mul_f32_e32 v10, v7, v8
	v_mul_f32_e32 v11, v5, v10
	v_fma_f32 v5, v10, v5, -v11
	v_fmac_f32_e32 v5, v10, v3
	v_sub_f32_e32 v3, v13, v8
	v_add_f32_e32 v3, v6, v3
	v_add_f32_e32 v6, v11, v5
	v_sub_f32_e32 v12, v8, v6
	v_sub_f32_e32 v8, v8, v12
	v_sub_f32_e32 v11, v6, v11
	v_sub_f32_e32 v6, v8, v6
	v_add_f32_e32 v3, v3, v6
	v_sub_f32_e32 v5, v11, v5
	v_add_f32_e32 v3, v5, v3
	v_add_f32_e32 v5, v9, v10
	v_add_f32_e32 v3, v12, v3
	v_sub_f32_e32 v6, v5, v9
	v_mul_f32_e32 v3, v7, v3
	v_sub_f32_e32 v6, v10, v6
	v_add_f32_e32 v3, v6, v3
	v_mul_f32_e32 v9, 0x3f317218, v2
	v_add_f32_e32 v6, v5, v3
	v_fma_f32 v10, v2, s2, -v9
	v_mul_f32_e32 v7, v6, v6
	v_fmac_f32_e32 v10, 0xb102e308, v2
	v_sub_f32_e32 v2, v6, v5
	v_fmamk_f32 v8, v7, 0x3e9b6dac, v200
	v_sub_f32_e32 v2, v3, v2
	v_add_f32_e32 v3, v9, v10
	v_fmaak_f32 v8, v7, v8, 0x3f2aaada
	v_sub_f32_e32 v5, v3, v9
	v_ldexp_f32 v9, v6, 1
	v_mul_f32_e32 v6, v6, v7
	v_mul_f32_e32 v6, v6, v8
	v_add_f32_e32 v7, v9, v6
	v_sub_f32_e32 v8, v7, v9
	v_ldexp_f32 v2, v2, 1
	v_sub_f32_e32 v6, v6, v8
	v_add_f32_e32 v2, v2, v6
	v_add_f32_e32 v6, v7, v2
	v_sub_f32_e32 v7, v6, v7
	v_sub_f32_e32 v2, v2, v7
	v_add_f32_e32 v7, v3, v6
	v_sub_f32_e32 v8, v7, v3
	v_sub_f32_e32 v9, v7, v8
	v_sub_f32_e32 v5, v10, v5
	v_sub_f32_e32 v3, v3, v9
	v_sub_f32_e32 v6, v6, v8
	v_add_f32_e32 v3, v6, v3
	v_add_f32_e32 v6, v5, v2
	v_sub_f32_e32 v8, v6, v5
	v_sub_f32_e32 v9, v6, v8
	v_sub_f32_e32 v5, v5, v9
	v_sub_f32_e32 v2, v2, v8
	v_add_f32_e32 v3, v6, v3
	v_add_f32_e32 v2, v2, v5
	v_add_f32_e32 v5, v7, v3
	v_sub_f32_e32 v6, v5, v7
	v_sub_f32_e32 v3, v3, v6
	v_add_f32_e32 v2, v2, v3
	s_mov_b32 s2, 0x7f800000
	v_add_f32_e32 v2, v5, v2
	v_cmp_neq_f32_e32 vcc, s2, v4
	s_mov_b32 s2, 0x33800000
	v_add_u32_e32 v3, -1, v201
	v_cndmask_b32_e32 v2, v202, v2, vcc
	v_cmp_ngt_f32_e32 vcc, -1.0, v4
	s_nop 1
	v_cndmask_b32_e32 v2, v203, v2, vcc
	v_cmp_neq_f32_e32 vcc, -1.0, v4
	s_nop 1
	v_cndmask_b32_e32 v2, v204, v2, vcc
	v_cmp_lt_f32_e64 vcc, |v4|, s2
	s_lshl_b32 s2, s39, 2
	s_ashr_i32 s3, s2, 31
	v_cndmask_b32_e32 v2, v2, v4, vcc
	v_sub_f32_e32 v0, v0, v2
	v_mov_b32_e32 v4, v0
	s_nop 1
	v_add_f32_dpp v4, v0, v4 row_shr:1 row_mask:0xf bank_mask:0xf
	v_add_f32_dpp v4, v0, v4 row_shr:2 row_mask:0xf bank_mask:0xf
	v_add_f32_dpp v4, v0, v4 row_shr:3 row_mask:0xf bank_mask:0xf
	s_nop 1
	v_add_f32_dpp v4, v4, v4 row_shr:4 row_mask:0xf bank_mask:0xe
	s_nop 1
	v_add_f32_dpp v4, v4, v4 row_shr:8 row_mask:0xf bank_mask:0xc
	s_nop 1
	v_add_f32_dpp v4, v4, v4 row_bcast:15 row_mask:0xa bank_mask:0xf
	s_nop 1
	v_add_f32_dpp v4, v4, v4 row_bcast:31 row_mask:0xc bank_mask:0xf
	v_mov_b32_e32 v0, v4
	v_sub_f32_e32 v1, v1, v0
	v_mov_b32_e32 v3, v1
	s_nop 1
	v_max_f32_dpp v3, v1, v3 row_shr:1 row_mask:0xf bank_mask:0xf
	v_max_f32_dpp v3, v1, v3 row_shr:2 row_mask:0xf bank_mask:0xf
	v_max_f32_dpp v3, v1, v3 row_shr:3 row_mask:0xf bank_mask:0xf
	s_nop 1
	v_max_f32_dpp v3, v3, v3 row_shr:4 row_mask:0xf bank_mask:0xe
	s_nop 1
	v_max_f32_dpp v3, v3, v3 row_shr:8 row_mask:0xf bank_mask:0xc
	s_nop 1
	v_max_f32_dpp v3, v3, v3 row_bcast:15 row_mask:0xa bank_mask:0xf
	s_nop 1
	v_max_f32_dpp v3, v3, v3 row_bcast:31 row_mask:0xc bank_mask:0xf
	v_mov_b32_e32 v2, v3
	v_max_f32_e32 v2, v2, v2
	s_waitcnt vmcnt(8)
	v_mov_b32_e32 v3, v216
	v_max_f32_e32 v4, v3, v3
	v_max_f32_e32 v2, v4, v2
	v_lshl_add_u32 v4, v22, 2, 0
	v_add_u32_e32 v4, 0x19200, v4
	ds_write2st64_b32 v4, v1, v2 offset1:1
	v_sub_f32_e32 v1, v3, v2
	v_add_f32_e32 v0, v0, v2
	v_mul_f32_e32 v1, 0x3fb8aa3b, v1
	v_mul_f32_e32 v0, 0xbfb8aa3b, v0
	v_exp_f32_e32 v1, v1
	v_exp_f32_e32 v0, v0
	ds_write2st64_b32 v4, v1, v0 offset0:2 offset1:3
.LBB0_451:
	s_lshl_b32 s12, s42, 7
	v_mul_u32_u24_e32 v24, 0x90, v209
	v_add_u32_e32 v24, v24, v211
	s_waitcnt vmcnt(8)
	ds_write_b128 v24, v[44:47] offset:18432
	ds_write_b128 v24, v[48:51] offset:27648
	v_cmp_gt_i32_e32 vcc, s66, v23
	s_and_saveexec_b64 s[2:3], vcc
	v_cmp_gt_u32_e32 vcc, 8, v23
	s_nop 1
	v_cndmask_b32_e32 v2, 0, v205, vcc
	v_mov_b32_e32 v3, v2
	v_mov_b32_e32 v4, v2
	v_mov_b32_e32 v5, v2
	ds_write_b128 v24, v[2:5] offset:36864
	s_or_b64 exec, exec, s[2:3]
	ds_write_b128 v24, v[52:55] offset:39168
	ds_write_b128 v24, v[56:59] offset:48384
	v_cmp_gt_u32_e32 vcc, 8, v23
	s_and_saveexec_b64 s[2:3], vcc
	ds_write_b128 v24, v[60:63] offset:57600
	s_or_b64 exec, exec, s[2:3]
	s_movk_i32 s4, 0x78
	v_cmp_gt_i32_e32 vcc, s4, v23
	s_and_saveexec_b64 s[2:3], vcc
	v_mov_b32_e32 v2, 0
	v_mov_b32_e32 v3, 0
	v_mov_b32_e32 v4, 0
	v_mov_b32_e32 v5, 0
	ds_write_b128 v24, v[2:5] offset:57744
	s_or_b64 exec, exec, s[2:3]
	v_mov_b32_e32 v4, v64
	v_mov_b32_e32 v5, v65
	v_mov_b32_e32 v6, v66
	v_mov_b32_e32 v7, v67
	v_mov_b32_e32 v0, v68
	v_mov_b32_e32 v1, v69
	v_mov_b32_e32 v2, v70
	v_mov_b32_e32 v3, v71
	s_and_saveexec_b64 s[2:3], s[46:47]
	v_lshlrev_b32_e32 v12, 16, v80
	v_and_b32_e32 v13, 0xffff0000, v80
	v_pk_fma_f32 v[4:5], v[84:85], v[12:13], v[4:5]
	v_lshlrev_b32_e32 v14, 16, v81
	v_and_b32_e32 v15, 0xffff0000, v81
	v_pk_fma_f32 v[6:7], v[86:87], v[14:15], v[6:7]
	v_lshlrev_b32_e32 v12, 16, v82
	v_and_b32_e32 v13, 0xffff0000, v82
	v_pk_fma_f32 v[0:1], v[88:89], v[12:13], v[0:1]
	v_lshlrev_b32_e32 v14, 16, v83
	v_and_b32_e32 v15, 0xffff0000, v83
	v_pk_fma_f32 v[2:3], v[90:91], v[14:15], v[2:3]
	s_or_b64 exec, exec, s[2:3]
	s_and_saveexec_b64 s[2:3], s[48:49]
	v_lshlrev_b32_e32 v12, 16, v92
	v_and_b32_e32 v13, 0xffff0000, v92
	v_pk_fma_f32 v[4:5], v[96:97], v[12:13], v[4:5]
	v_lshlrev_b32_e32 v14, 16, v93
	v_and_b32_e32 v15, 0xffff0000, v93
	v_pk_fma_f32 v[6:7], v[98:99], v[14:15], v[6:7]
	v_lshlrev_b32_e32 v12, 16, v94
	v_and_b32_e32 v13, 0xffff0000, v94
	v_pk_fma_f32 v[0:1], v[100:101], v[12:13], v[0:1]
	v_lshlrev_b32_e32 v14, 16, v95
	v_and_b32_e32 v15, 0xffff0000, v95
	v_pk_fma_f32 v[2:3], v[102:103], v[14:15], v[2:3]
	s_or_b64 exec, exec, s[2:3]
	s_and_saveexec_b64 s[2:3], s[50:51]
	v_lshlrev_b32_e32 v12, 16, v104
	v_and_b32_e32 v13, 0xffff0000, v104
	v_pk_fma_f32 v[4:5], v[108:109], v[12:13], v[4:5]
	v_lshlrev_b32_e32 v14, 16, v105
	v_and_b32_e32 v15, 0xffff0000, v105
	v_pk_fma_f32 v[6:7], v[110:111], v[14:15], v[6:7]
	v_lshlrev_b32_e32 v12, 16, v106
	v_and_b32_e32 v13, 0xffff0000, v106
	v_pk_fma_f32 v[0:1], v[112:113], v[12:13], v[0:1]
	v_lshlrev_b32_e32 v14, 16, v107
	v_and_b32_e32 v15, 0xffff0000, v107
	v_pk_fma_f32 v[2:3], v[114:115], v[14:15], v[2:3]
	s_or_b64 exec, exec, s[2:3]
	v_lshlrev_b32_e32 v12, 16, v116
	v_and_b32_e32 v13, 0xffff0000, v116
	v_pk_fma_f32 v[4:5], v[120:121], v[12:13], v[4:5]
	v_lshlrev_b32_e32 v14, 16, v117
	v_and_b32_e32 v15, 0xffff0000, v117
	v_pk_fma_f32 v[6:7], v[122:123], v[14:15], v[6:7]
	v_lshlrev_b32_e32 v12, 16, v118
	v_and_b32_e32 v13, 0xffff0000, v118
	v_pk_fma_f32 v[0:1], v[124:125], v[12:13], v[0:1]
	v_lshlrev_b32_e32 v14, 16, v119
	v_and_b32_e32 v15, 0xffff0000, v119
	v_pk_fma_f32 v[2:3], v[126:127], v[14:15], v[2:3]
	v_mul_f32_e32 v20, 0xbfb8aa3b, v4
	v_mul_f32_e32 v21, 0xbfb8aa3b, v5
	v_mul_f32_e32 v26, 0xbfb8aa3b, v6
	v_mul_f32_e32 v27, 0xbfb8aa3b, v7
	v_mul_f32_e32 v28, 0xbfb8aa3b, v0
	v_mul_f32_e32 v29, 0xbfb8aa3b, v1
	v_exp_f32_e32 v20, v20
	v_exp_f32_e32 v21, v21
	v_exp_f32_e32 v26, v26
	v_exp_f32_e32 v27, v27
	v_exp_f32_e32 v28, v28
	v_exp_f32_e32 v29, v29
	v_mul_f32_e32 v30, 0xbfb8aa3b, v2
	v_mul_f32_e32 v31, 0xbfb8aa3b, v3
	v_exp_f32_e32 v30, v30
	v_exp_f32_e32 v31, v31
	v_add_f32_e32 v20, 1.0, v20
	v_add_f32_e32 v21, 1.0, v21
	v_add_f32_e32 v26, 1.0, v26
	v_add_f32_e32 v27, 1.0, v27
	v_add_f32_e32 v28, 1.0, v28
	v_add_f32_e32 v29, 1.0, v29
	v_rcp_f32_e32 v20, v20
	v_rcp_f32_e32 v21, v21
	v_rcp_f32_e32 v26, v26
	v_rcp_f32_e32 v27, v27
	v_rcp_f32_e32 v28, v28
	v_rcp_f32_e32 v29, v29
	v_add_f32_e32 v30, 1.0, v30
	v_add_f32_e32 v31, 1.0, v31
	v_rcp_f32_e32 v30, v30
	v_rcp_f32_e32 v31, v31
	v_pk_mul_f32 v[4:5], v[4:5], v[20:21]
	s_mov_b32 s10, 0x3e000000
	v_pk_mul_f32 v[6:7], v[6:7], v[26:27]
	v_pk_mul_f32 v[0:1], v[0:1], v[28:29]
	v_pk_mul_f32 v[4:5], v[4:5], s[10:11] op_sel_hi:[1,0]
	v_pk_mul_f32 v[6:7], v[6:7], s[10:11] op_sel_hi:[1,0]
	v_pk_mul_f32 v[0:1], v[0:1], s[10:11] op_sel_hi:[1,0]
	v_cvt_pk_bf16_f32 v4, v4, v5
	v_cvt_pk_bf16_f32 v5, v6, v7
	v_cvt_pk_bf16_f32 v6, v0, v1
	v_pk_mul_f32 v[0:1], v[2:3], v[30:31]
	v_pk_mul_f32 v[0:1], v[0:1], s[10:11] op_sel_hi:[1,0]
	v_cvt_pk_bf16_f32 v7, v0, v1
	ds_write_b128 v24, v[4:7]
	v_mov_b32_e32 v4, v72
	v_mov_b32_e32 v5, v73
	v_mov_b32_e32 v6, v74
	v_mov_b32_e32 v7, v75
	v_mov_b32_e32 v0, v76
	v_mov_b32_e32 v1, v77
	v_mov_b32_e32 v2, v78
	v_mov_b32_e32 v3, v79
	s_and_saveexec_b64 s[2:3], s[46:47]
	v_lshlrev_b32_e32 v12, 16, v128
	v_and_b32_e32 v13, 0xffff0000, v128
	v_pk_fma_f32 v[4:5], v[132:133], v[12:13], v[4:5]
	v_lshlrev_b32_e32 v14, 16, v129
	v_and_b32_e32 v15, 0xffff0000, v129
	v_pk_fma_f32 v[6:7], v[134:135], v[14:15], v[6:7]
	v_lshlrev_b32_e32 v12, 16, v130
	v_and_b32_e32 v13, 0xffff0000, v130
	v_pk_fma_f32 v[0:1], v[136:137], v[12:13], v[0:1]
	v_lshlrev_b32_e32 v14, 16, v131
	v_and_b32_e32 v15, 0xffff0000, v131
	v_pk_fma_f32 v[2:3], v[138:139], v[14:15], v[2:3]
	s_or_b64 exec, exec, s[2:3]
	s_and_saveexec_b64 s[2:3], s[48:49]
	v_lshlrev_b32_e32 v12, 16, v140
	v_and_b32_e32 v13, 0xffff0000, v140
	v_pk_fma_f32 v[4:5], v[144:145], v[12:13], v[4:5]
	v_lshlrev_b32_e32 v14, 16, v141
	v_and_b32_e32 v15, 0xffff0000, v141
	v_pk_fma_f32 v[6:7], v[146:147], v[14:15], v[6:7]
	v_lshlrev_b32_e32 v12, 16, v142
	v_and_b32_e32 v13, 0xffff0000, v142
	v_pk_fma_f32 v[0:1], v[148:149], v[12:13], v[0:1]
	v_lshlrev_b32_e32 v14, 16, v143
	v_and_b32_e32 v15, 0xffff0000, v143
	v_pk_fma_f32 v[2:3], v[150:151], v[14:15], v[2:3]
	s_or_b64 exec, exec, s[2:3]
	s_and_saveexec_b64 s[2:3], s[50:51]
	v_lshlrev_b32_e32 v12, 16, v152
	v_and_b32_e32 v13, 0xffff0000, v152
	v_pk_fma_f32 v[4:5], v[156:157], v[12:13], v[4:5]
	v_lshlrev_b32_e32 v14, 16, v153
	v_and_b32_e32 v15, 0xffff0000, v153
	v_pk_fma_f32 v[6:7], v[158:159], v[14:15], v[6:7]
	v_lshlrev_b32_e32 v12, 16, v154
	v_and_b32_e32 v13, 0xffff0000, v154
	v_pk_fma_f32 v[0:1], v[160:161], v[12:13], v[0:1]
	v_lshlrev_b32_e32 v14, 16, v155
	v_and_b32_e32 v15, 0xffff0000, v155
	v_pk_fma_f32 v[2:3], v[162:163], v[14:15], v[2:3]
	s_or_b64 exec, exec, s[2:3]
	v_lshlrev_b32_e32 v12, 16, v178
	v_and_b32_e32 v13, 0xffff0000, v178
	v_pk_fma_f32 v[4:5], v[182:183], v[12:13], v[4:5]
	v_lshlrev_b32_e32 v14, 16, v179
	v_and_b32_e32 v15, 0xffff0000, v179
	v_pk_fma_f32 v[6:7], v[184:185], v[14:15], v[6:7]
	v_lshlrev_b32_e32 v12, 16, v180
	v_and_b32_e32 v13, 0xffff0000, v180
	v_pk_fma_f32 v[0:1], v[186:187], v[12:13], v[0:1]
	v_lshlrev_b32_e32 v14, 16, v181
	v_and_b32_e32 v15, 0xffff0000, v181
	v_pk_fma_f32 v[2:3], v[188:189], v[14:15], v[2:3]
	v_mov_b32_e32 v236, v224
	v_mov_b32_e32 v237, v225
	v_mov_b32_e32 v238, v226
	v_mov_b32_e32 v239, v227
	v_mov_b32_e32 v240, v228
	v_mov_b32_e32 v241, v229
	v_mov_b32_e32 v242, v230
	v_mov_b32_e32 v243, v231
	v_mov_b64_e32 v[244:245], v[234:235]
	s_add_i32 s56, s39, s71
	s_cmpk_gt_i32 s56, 0x7ff
	s_cbranch_scc1 .Lm3_pf_end
	s_ashr_i32 s98, s56, 10
	s_ashr_i32 s99, s98, 31
	s_lshl_b64 s[98:99], s[98:99], 13
	s_and_b32 s100, s56, 0x7f
	s_lshl_b32 s90, s100, 6
	s_or_b32 s98, s98, s90
	s_bfe_u32 s57, s56, 0x30007
	v_readfirstlane_b32 s101, v194
	v_lshrrev_b32_e32 v209, 3, v194
	v_and_b32_e32 v210, 7, v194
	v_lshlrev_b32_e32 v211, 4, v210
	v_lshl_or_b32 v190, v209, 15, v211
	v_lshlrev_b32_e32 v191, 4, v194
	v_lshl_or_b32 v192, v209, 11, v211
	v_add_u32_e32 v193, 0x1000, v192
	v_lshlrev_b32_e32 v208, 5, v210
	s_lshl_b32 s90, s57, 7
	s_or_b32 s90, s90, 0x400
	s_lshl_b64 s[52:53], s[98:99], 1
	s_add_u32 s52, s33, s52
	s_addc_u32 s53, s36, s53
	s_lshl_b32 s91, s90, 15
	s_add_u32 s52, s52, s91
	s_addc_u32 s53, s53, 0
	s_add_u32 s54, s52, 0x200000
	s_addc_u32 s55, s53, 0
	global_load_dwordx4 v[44:47], v190, s[52:53]
	global_load_dwordx4 v[48:51], v190, s[54:55]
	s_mul_i32 s92, s56, 0x4080
	s_mul_hi_i32 s93, s56, 0x4080
	s_add_u32 s92, s37, s92
	s_addc_u32 s93, s38, s93
	global_load_dwordx4 v[52:55], v191, s[92:93]
	s_add_u32 s94, s92, 0x2000
	s_addc_u32 s95, s93, 0
	global_load_dwordx4 v[56:59], v191, s[94:95]
	s_add_u32 s94, s92, 0x4000
	s_addc_u32 s95, s93, 0
	v_cmp_gt_u32_e32 vcc, 8, v194
	s_and_saveexec_b64 s[96:97], vcc
	global_load_dwordx4 v[60:63], v191, s[94:95]
	s_mov_b64 exec, s[96:97]
	s_lshl_b32 s91, s57, 8
	s_add_u32 s94, s18, s91
	s_addc_u32 s95, s19, 0
	global_load_dwordx4 v[64:67], v208, s[94:95]
	global_load_dwordx4 v[68:71], v208, s[94:95] offset:16
	global_load_dwordx4 v[72:75], v208, s[94:95] offset:2048
	global_load_dwordx4 v[76:79], v208, s[94:95] offset:2064
	s_add_u32 s94, s16, s91
	s_addc_u32 s95, s17, 0
	global_load_dwordx4 v[84:87], v208, s[94:95]
	global_load_dwordx4 v[88:91], v208, s[94:95] offset:16
	global_load_dwordx4 v[132:135], v208, s[94:95] offset:2048
	global_load_dwordx4 v[136:139], v208, s[94:95] offset:2064
	s_add_u32 s94, s94, 0x1000
	s_addc_u32 s95, s95, 0
	global_load_dwordx4 v[96:99], v208, s[94:95]
	global_load_dwordx4 v[100:103], v208, s[94:95] offset:16
	global_load_dwordx4 v[144:147], v208, s[94:95] offset:2048
	global_load_dwordx4 v[148:151], v208, s[94:95] offset:2064
	s_add_u32 s94, s94, 0x1000
	s_addc_u32 s95, s95, 0
	global_load_dwordx4 v[108:111], v208, s[94:95]
	global_load_dwordx4 v[112:115], v208, s[94:95] offset:16
	global_load_dwordx4 v[156:159], v208, s[94:95] offset:2048
	global_load_dwordx4 v[160:163], v208, s[94:95] offset:2064
	s_add_u32 s94, s94, 0x1000
	s_addc_u32 s95, s95, 0
	global_load_dwordx4 v[120:123], v208, s[94:95]
	global_load_dwordx4 v[124:127], v208, s[94:95] offset:16
	global_load_dwordx4 v[182:185], v208, s[94:95] offset:2048
	global_load_dwordx4 v[186:189], v208, s[94:95] offset:2064
	s_sub_u32 s92, s98, 3
	s_subb_u32 s93, s99, 0
	s_lshl_b64 s[92:93], s[92:93], 11
	s_add_u32 s92, s14, s92
	s_addc_u32 s93, s15, s93
	s_lshl_b32 s91, s57, 7
	s_add_u32 s92, s92, s91
	s_addc_u32 s93, s93, 0
	s_cmp_lg_u32 s100, 0
	s_cselect_b64 s[54:55], -1, 0
	v_cmp_lt_u32_e32 vcc, 2, v209
	s_or_b64 s[46:47], s[54:55], vcc
	v_cmp_lt_u32_e32 vcc, 1, v209
	s_or_b64 s[48:49], s[54:55], vcc
	v_cmp_lt_u32_e32 vcc, 0, v209
	s_or_b64 s[50:51], s[54:55], vcc
	s_mov_b64 s[96:97], exec
	s_and_b64 exec, s[96:97], s[46:47]
	global_load_dwordx4 v[80:83], v192, s[92:93]
	global_load_dwordx4 v[128:131], v192, s[92:93] offset:1024
	s_and_b64 exec, s[96:97], s[48:49]
	global_load_dwordx4 v[92:95], v192, s[92:93] offset:2048
	global_load_dwordx4 v[140:143], v192, s[92:93] offset:3072
	s_and_b64 exec, s[96:97], s[50:51]
	global_load_dwordx4 v[104:107], v193, s[92:93]
	global_load_dwordx4 v[152:155], v193, s[92:93] offset:1024
	s_mov_b64 exec, s[96:97]
	global_load_dwordx4 v[116:119], v193, s[92:93] offset:2048
	global_load_dwordx4 v[178:181], v193, s[92:93] offset:3072
	s_lshr_b32 s90, s101, 6
	s_lshl_b32 s90, s90, 3
	s_add_u32 s90, s98, s90
	s_addc_u32 s91, s99, 0
	s_lshl_b64 s[90:91], s[90:91], 11
	s_add_u32 s90, s22, s90
	s_addc_u32 s91, s23, s91
	s_lshl_b32 s92, s57, 8
	v_and_b32_e32 v232, 63, v194
	v_lshlrev_b32_e32 v233, 3, v232
	v_lshl_or_b32 v232, v232, 2, s92
	global_load_dword v224, v232, s[90:91]
	global_load_dword v225, v232, s[90:91] offset:2048
	s_add_u32 s90, s90, 0x1000
	s_addc_u32 s91, s91, 0
	global_load_dword v226, v232, s[90:91]
	global_load_dword v227, v232, s[90:91] offset:2048
	s_add_u32 s90, s90, 0x1000
	s_addc_u32 s91, s91, 0
	global_load_dword v228, v232, s[90:91]
	global_load_dword v229, v232, s[90:91] offset:2048
	s_add_u32 s90, s90, 0x1000
	s_addc_u32 s91, s91, 0
	global_load_dword v230, v232, s[90:91]
	global_load_dword v231, v232, s[90:91] offset:2048
	global_load_dwordx2 v[234:235], v233, s[20:21]
	s_cmp_gt_u32 s101, 63
	s_cbranch_scc1 .Lm3_pf_nog_b
	v_and_b32_e32 v217, 63, v194
	v_or_b32_e32 v218, s98, v217
	v_mov_b32_e32 v219, s99
	v_lshlrev_b64 v[218:219], 6, v[218:219]
	v_lshl_add_u64 v[218:219], s[30:31], 0, v[218:219]
	s_lshl_b32 s90, s57, 2
	s_mov_b32 s91, 0
	v_lshl_add_u64 v[218:219], v[218:219], 0, s[90:91]
	v_mov_b32_e32 v220, s90
	global_load_dword v212, v[218:219], off offset:32
	global_load_dword v213, v220, s[26:27]
	global_load_dword v214, v[218:219], off
	global_load_dword v215, v220, s[28:29]
	s_lshl_b32 s90, s56, 4
	s_add_u32 s90, s0, s90
	s_addc_u32 s91, s1, 0
	v_mov_b32_e32 v221, 0x18100000
	global_load_dword v216, v221, s[90:91] offset:8
.Lm3_pf_nog_b:
.Lm3_pf_end:
	v_mul_f32_e32 v8, 0xbfb8aa3b, v4
	v_exp_f32_e32 v8, v8
	s_bfe_u32 s5, s40, 0x20006
	v_and_b32_e32 v9, 15, v23
	s_ashr_i32 s6, s40, 7
	v_add_f32_e32 v8, 1.0, v8
	v_rcp_f32_e32 v10, v8
	v_mul_f32_e32 v8, 0xbfb8aa3b, v5
	v_exp_f32_e32 v8, v8
	s_lshl_b32 s4, s5, 4
	s_and_b32 s2, s6, -2
	s_cmp_gt_i32 s2, s5
	v_add_f32_e32 v8, 1.0, v8
	v_rcp_f32_e32 v11, v8
	v_mul_f32_e32 v8, 0xbfb8aa3b, v6
	v_exp_f32_e32 v8, v8
	v_pk_mul_f32 v[4:5], v[4:5], v[10:11]
	v_add_f32_e32 v8, 1.0, v8
	v_rcp_f32_e32 v10, v8
	v_mul_f32_e32 v8, 0xbfb8aa3b, v7
	v_exp_f32_e32 v8, v8
	s_nop 0
	v_add_f32_e32 v8, 1.0, v8
	v_rcp_f32_e32 v11, v8
	v_mul_f32_e32 v8, 0xbfb8aa3b, v0
	v_exp_f32_e32 v8, v8
	v_pk_mul_f32 v[6:7], v[6:7], v[10:11]
	v_add_f32_e32 v8, 1.0, v8
	v_rcp_f32_e32 v10, v8
	v_mul_f32_e32 v8, 0xbfb8aa3b, v1
	v_exp_f32_e32 v8, v8
	s_nop 0
	v_add_f32_e32 v8, 1.0, v8
	v_rcp_f32_e32 v11, v8
	s_nop 0
	v_pk_mul_f32 v[10:11], v[0:1], v[10:11]
	v_mul_f32_e32 v0, 0xbfb8aa3b, v2
	v_mul_f32_e32 v1, 0xbfb8aa3b, v3
	v_exp_f32_e32 v0, v0
	v_exp_f32_e32 v1, v1
	v_add_f32_e32 v0, 1.0, v0
	v_add_f32_e32 v1, 1.0, v1
	v_rcp_f32_e32 v0, v0
	v_rcp_f32_e32 v1, v1
	s_nop 0
	v_pk_mul_f32 v[12:13], v[2:3], v[0:1]
	v_cvt_pk_bf16_f32 v0, v4, v5
	v_cvt_pk_bf16_f32 v1, v6, v7
	v_cvt_pk_bf16_f32 v2, v10, v11
	v_cvt_pk_bf16_f32 v3, v12, v13
	ds_write_b128 v24, v[0:3] offset:9216
	v_and_b32_e32 v1, 48, v22
	v_or_b32_e32 v0, s4, v9
	v_add_u32_e32 v8, 0, v1
	v_mad_u32_u24 v10, v0, s84, v8
	v_lshl_or_b32 v12, s2, 4, v9
	v_mov_b32_e32 v5, 0
	v_mov_b32_e32 v0, 0
	v_mov_b32_e32 v1, 0
	v_mov_b32_e32 v2, 0
	v_mov_b32_e32 v3, 0
	s_waitcnt lgkmcnt(0)
	s_barrier
	s_cbranch_scc1 .LBB0_474
	v_mad_u64_u32 v[6:7], s[2:3], v12, s84, v[8:9]
	ds_read_b128 v[0:3], v10
	ds_read_b128 v[14:17], v6 offset:9216
	s_waitcnt lgkmcnt(0)
	v_mfma_f32_16x16x32_bf16 v[0:3], v[0:3], v[14:17], 0
	ds_read_b128 v[14:17], v10 offset:64
	ds_read_b128 v[18:21], v6 offset:9280
	s_waitcnt lgkmcnt(0)
	v_mfma_f32_16x16x32_bf16 v[0:3], v[14:17], v[18:21], v[0:3]
